# unit-loop top (in-proj A, INB): next unit's tile decode by shifts (group height is always WGM=4) instead of the generic float-reciprocal integer division chain; on top of v88
# speedup vs baseline: 1.0009x; 1.0009x over previous
;     __host__ __device__ bool next(int i, Unit& u) const {
;         const long L = (long)i * G + c; if (L >= nwg) return false;
;         int wgid = (int)L; { const int q = nwg / NXCD, r = nwg % NXCD, xcd = wgid % NXCD, off = wgid / NXCD; wgid = (xcd < r ? xcd * (q + 1) : r * (q + 1) + (xcd - r) * q) + off; }
;         const int nig = WGM * nN, gid = wgid / nig, fm = gid * WGM, gsz = (nM - fm) < WGM ? (nM - fm) : WGM;
;         u.pm = fm + ((wgid % nig) % gsz); u.pn = (wgid % nig) / gsz; return true;
;     }
;     ...
;         const bool has_next = S.next(ui + 1, nxt);
;         const char* nA = has_next ? (const char*)g.A + (size_t)nxt.pm * tstep : cA; const char* nB = has_next ? (const char*)g.Bt + (size_t)nxt.pn * tstep : cB;
.LBB0_203:
	s_add_i32 s42, s27, 1
	v_readlane_b32 s2, v252, 17
	s_mul_i32 s2, s42, s2
	s_mul_hi_u32 s29, s42, s3
	s_add_i32 s29, s29, s2
	s_mul_i32 s2, s42, s3
	s_add_u32 s48, s2, s87
	v_readlane_b32 s2, v253, 59
	s_addc_u32 s49, s29, s2
	v_cmp_gt_i64_e32 vcc, s[48:49], v[164:165]
	v_cmp_lt_i64_e64 s[36:37], s[48:49], v[162:163]
	s_cbranch_vccnz .LBB0_205
	s_ashr_i32 s2, s48, 31
	s_lshr_b32 s2, s2, 29
	s_add_i32 s2, s48, s2
	s_ashr_i32 s28, s2, 3
	s_and_b32 s2, s2, -8
	s_sub_i32 s2, s48, s2
	s_cmp_lt_i32 s2, 0
	s_movk_i32 s29, 0xa1
	s_cselect_b32 s29, s29, 0xa0
	s_mul_i32 s2, s2, s29
	s_add_i32 s2, s2, s28
	s_mul_hi_i32 s28, s2, 0x66666667
	s_lshr_b32 s29, s28, 31
	s_ashr_i32 s28, s28, 6
	s_add_i32 s28, s28, s29
	s_lshl_b32 s29, s28, 2
	s_waitcnt lgkmcnt(0)
	s_mulk_i32 s28, 0xa0
	s_sub_i32 s2, s2, s28
	s_ashr_i32 s28, s2, 2
	s_and_b32 s2, s2, 3
	s_add_i32 s30, s29, s2

;     __host__ __device__ bool next(int i, Unit& u) const {
;         const long L = (long)i * G + c; if (L >= nwg) return false;
;         int wgid = (int)L; { const int q = nwg / NXCD, r = nwg % NXCD, xcd = wgid % NXCD, off = wgid / NXCD; wgid = (xcd < r ? xcd * (q + 1) : r * (q + 1) + (xcd - r) * q) + off; }
;         const int nig = WGM * nN, gid = wgid / nig, fm = gid * WGM, gsz = (nM - fm) < WGM ? (nM - fm) : WGM;
;         u.pm = fm + ((wgid % nig) % gsz); u.pn = (wgid % nig) / gsz; return true;
;     }
.LBB0_530:
	s_ashr_i32 s2, s2, 3
	s_add_i32 s2, s16, s2
	s_ashr_i32 s5, s2, 31
	s_lshr_b32 s5, s5, 26
	s_add_i32 s5, s2, s5
	s_ashr_i32 s6, s5, 6
	s_lshl_b32 s6, s6, 2
	s_waitcnt lgkmcnt(0)
	s_and_b32 s5, s5, 0xffffffc0
	s_sub_i32 s2, s2, s5
	s_ashr_i32 s16, s2, 2
	s_and_b32 s2, s2, 3
	s_add_i32 s6, s6, s2
